# remaining s_sleep 1 in the two pre-loop barrier instances removed as well (all barrier polls spin)
# baseline (speedup 1.0000x reference)
; DI unsigned xb_ld(unsigned* p) { return __hip_atomic_load(p, __ATOMIC_RELAXED, __HIP_MEMORY_SCOPE_AGENT); }
; DI void xcd_barrier_complete(unsigned* bar, unsigned x, unsigned& nloc, unsigned& nx) {
;     ...
;   for (;;) {
;     sum = 0u; cnt = 0u; mine = 0u;
; #pragma unroll
;     for (unsigned j = 0; j < 16; ++j) { const unsigned c = xb_ld(&bar[XB_XCNT(j)]); sum += c; cnt += (c > 0u) ? 1u : 0u; mine = (j == x) ? c : mine; }
;     if (sum == G) break;
;     __builtin_amdgcn_s_sleep(1);
;   }
.Lgs_92:
	global_load_dword v15, v16, s[2:3] sc1
	s_waitcnt lgkmcnt(0)
	global_load_dword v0, v16, s[4:5] sc1
	global_load_dword v1, v16, s[6:7] sc1
	global_load_dword v2, v16, s[8:9] sc1
	global_load_dword v3, v16, s[10:11] sc1
	global_load_dword v4, v16, s[12:13] sc1
	global_load_dword v5, v16, s[14:15] sc1
	global_load_dword v6, v16, s[16:17] sc1
	global_load_dword v7, v16, s[18:19] sc1
	global_load_dword v8, v16, s[20:21] sc1
	global_load_dword v9, v16, s[22:23] sc1
	global_load_dword v10, v16, s[24:25] sc1
	global_load_dword v11, v16, s[26:27] sc1
	global_load_dword v12, v16, s[28:29] sc1
	global_load_dword v13, v16, s[30:31] sc1
	global_load_dword v14, v16, s[34:35] sc1
	s_mov_b64 s[36:37], -1
	s_waitcnt vmcnt(14)
	v_add_u32_e32 v17, v0, v15
	s_waitcnt vmcnt(13)
	v_add_u32_e32 v17, v17, v1
	s_waitcnt vmcnt(12)
	v_add_u32_e32 v17, v17, v2
	s_waitcnt vmcnt(11)
	v_add_u32_e32 v17, v17, v3
	s_waitcnt vmcnt(10)
	v_add_u32_e32 v17, v17, v4
	s_waitcnt vmcnt(9)
	v_add_u32_e32 v17, v17, v5
	s_waitcnt vmcnt(8)
	v_add_u32_e32 v17, v17, v6
	s_waitcnt vmcnt(7)
	v_add_u32_e32 v17, v17, v7
	s_waitcnt vmcnt(6)
	v_add_u32_e32 v17, v17, v8
	s_waitcnt vmcnt(5)
	v_add_u32_e32 v17, v17, v9
	s_waitcnt vmcnt(4)
	v_add_u32_e32 v17, v17, v10
	s_waitcnt vmcnt(3)
	v_add_u32_e32 v17, v17, v11
	s_waitcnt vmcnt(2)
	v_add_u32_e32 v17, v17, v12
	s_waitcnt vmcnt(1)
	v_add_u32_e32 v17, v17, v13
	s_waitcnt vmcnt(0)
	v_add_u32_e32 v17, v17, v14
	v_cmp_eq_u32_e32 vcc, s55, v17
	s_cbranch_vccnz .Lgs_91
	s_mov_b64 s[36:37], 0
	s_branch .Lgs_91

; DI unsigned xb_ld(unsigned* p) { return __hip_atomic_load(p, __ATOMIC_RELAXED, __HIP_MEMORY_SCOPE_AGENT); }
; DI void xcd_barrier(const XcdBarrier& b) {
;     ...
;       while (xb_ld(&bar[XB_XGEN(bx)]) == gen) __builtin_amdgcn_s_sleep(1);
.Lgs_100:
	global_load_dword v1, v0, s[4:5] sc1
	s_waitcnt vmcnt(0)
	v_cmp_ne_u32_e32 vcc, v1, v2
	s_or_b64 s[8:9], vcc, s[8:9]
	s_andn2_b64 exec, exec, s[8:9]
	s_cbranch_execnz .Lgs_100

; DI unsigned xb_ld(unsigned* p) { return __hip_atomic_load(p, __ATOMIC_RELAXED, __HIP_MEMORY_SCOPE_AGENT); }
; DI void xcd_barrier(const XcdBarrier& b) {
;     ...
;       else { while (xb_ld(&bar[XB_TOPGEN]) == tg) __builtin_amdgcn_s_sleep(1); }
.Lgs_108:
	global_load_dword v2, v0, s[2:3] sc1
	s_waitcnt vmcnt(0)
	v_cmp_ne_u32_e32 vcc, v2, v1
	s_or_b64 s[8:9], vcc, s[8:9]
	s_andn2_b64 exec, exec, s[8:9]
	s_cbranch_execnz .Lgs_108
